# v99 + converter workgroups rate-limited during GEMM1 (s_sleep 40 per weight item) so their traffic is spread over the whole phase
# speedup vs baseline: 1.0025x; 1.0025x over previous
.LBB0_80:
	s_cmp_lg_u32 s101, 2
	s_cbranch_scc1 .Lp0_nothr
	s_sleep 40
